# P8 tail task: hoisted row loads + DPP wave-sum; P1 SW table grouped loads; P9 prologue loads merged
# speedup vs baseline: 1.0251x; 1.0116x over previous
.LBB0_228:
	s_lshr_b32 s11, s9, 5
	s_lshr_b32 s34, s9, 3
	s_and_b32 s11, s11, 0x7fffff8
	s_and_b32 s34, s34, 4
	s_or_b32 s11, s11, s34
	s_bfe_u32 s34, s9, 0x20006
	s_or_b32 s11, s11, s34
	s_lshl_b32 s11, s11, 5
	s_and_b32 s34, s9, 31
	s_or_b32 s34, s11, s34
	s_ashr_i32 s35, s34, 31
	s_lshl_b64 s[34:35], s[34:35], 11
	v_lshl_add_u64 v[4:5], v[2:3], 0, s[34:35]
	global_load_dwordx4 v[22:25], v[4:5], off
	s_waitcnt lgkmcnt(0)
	global_load_dwordx4 v[26:29], v[4:5], off offset:16
	s_mov_b64 s[46:47], 0x18000
	s_mov_b32 s11, 5
	v_mov_b64_e32 v[4:5], v[0:1]
	s_mov_b64 s[34:35], s[4:5]
	s_waitcnt vmcnt(1)
	v_lshlrev_b32_e32 v12, 16, v22
	v_and_b32_e32 v13, 0xffff0000, v22
	s_waitcnt vmcnt(0)
	v_lshlrev_b32_e32 v14, 16, v26
	v_and_b32_e32 v15, 0xffff0000, v26
	v_lshlrev_b32_e32 v16, 16, v23
	v_and_b32_e32 v17, 0xffff0000, v23
	v_lshlrev_b32_e32 v18, 16, v27
	v_and_b32_e32 v19, 0xffff0000, v27
	v_lshlrev_b32_e32 v20, 16, v24
	v_and_b32_e32 v21, 0xffff0000, v24
	v_lshlrev_b32_e32 v22, 16, v28
	v_and_b32_e32 v23, 0xffff0000, v28
	v_lshlrev_b32_e32 v24, 16, v25
	v_and_b32_e32 v25, 0xffff0000, v25
	v_lshlrev_b32_e32 v26, 16, v29
	v_and_b32_e32 v27, 0xffff0000, v29
	s_branch .LBB0_230
.LBB0_230:
	v_lshl_add_u64 v[44:45], s[18:19], 0, v[4:5]
	v_lshl_add_u64 v[44:45], v[44:45], 0, s[14:15]
	global_load_dwordx4 v[48:51], v[44:45], off
	global_load_dwordx4 v[52:55], v[44:45], off offset:16
	global_load_dwordx4 v[56:59], v[44:45], off offset:32
	global_load_dwordx4 v[60:63], v[44:45], off offset:48
	v_lshl_add_u64 v[44:45], v[44:45], 0, s[30:31]
	global_load_dwordx4 v[64:67], v[44:45], off
	global_load_dwordx4 v[68:71], v[44:45], off offset:16
	global_load_dwordx4 v[72:75], v[44:45], off offset:32
	global_load_dwordx4 v[76:79], v[44:45], off offset:48
	v_lshl_add_u64 v[44:45], v[44:45], 0, s[30:31]
	global_load_dwordx4 v[80:83], v[44:45], off
	global_load_dwordx4 v[84:87], v[44:45], off offset:16
	global_load_dwordx4 v[88:91], v[44:45], off offset:32
	global_load_dwordx4 v[92:95], v[44:45], off offset:48
	v_lshl_add_u64 v[44:45], v[44:45], 0, s[30:31]
	global_load_dwordx4 v[96:99], v[44:45], off
	global_load_dwordx4 v[100:103], v[44:45], off offset:16
	global_load_dwordx4 v[104:107], v[44:45], off offset:32
	global_load_dwordx4 v[108:111], v[44:45], off offset:48
	v_lshl_add_u64 v[44:45], v[44:45], 0, s[30:31]
	global_load_dwordx4 v[112:115], v[44:45], off
	global_load_dwordx4 v[116:119], v[44:45], off offset:16
	global_load_dwordx4 v[120:123], v[44:45], off offset:32
	global_load_dwordx4 v[124:127], v[44:45], off offset:48
	v_lshl_add_u64 v[44:45], v[44:45], 0, s[30:31]
	global_load_dwordx4 v[128:131], v[44:45], off
	global_load_dwordx4 v[132:135], v[44:45], off offset:16
	global_load_dwordx4 v[136:139], v[44:45], off offset:32
	global_load_dwordx4 v[140:143], v[44:45], off offset:48
	v_lshl_add_u64 v[44:45], v[44:45], 0, s[30:31]
	global_load_dwordx4 v[144:147], v[44:45], off
	global_load_dwordx4 v[148:151], v[44:45], off offset:16
	global_load_dwordx4 v[152:155], v[44:45], off offset:32
	global_load_dwordx4 v[156:159], v[44:45], off offset:48
	v_lshl_add_u64 v[44:45], v[44:45], 0, s[30:31]
	global_load_dwordx4 v[160:163], v[44:45], off
	global_load_dwordx4 v[164:167], v[44:45], off offset:16
	global_load_dwordx4 v[168:171], v[44:45], off offset:32
	global_load_dwordx4 v[172:175], v[44:45], off offset:48
	s_waitcnt vmcnt(28)
	v_mul_f32_e32 v57, v57, v15
	v_mul_f32_e32 v59, v59, v19
	v_mul_f32_e32 v49, v49, v13
	v_mul_f32_e32 v51, v51, v17
	v_mul_f32_e32 v53, v53, v21
	v_mul_f32_e32 v55, v55, v25
	v_fmac_f32_e32 v57, v56, v14
	v_fmac_f32_e32 v59, v58, v18
	v_fmac_f32_e32 v49, v48, v12
	v_fmac_f32_e32 v51, v50, v16
	v_fmac_f32_e32 v53, v52, v20
	v_fmac_f32_e32 v55, v54, v24
	v_add_f32_e32 v57, v57, v59
	v_add_f32_e32 v59, v49, v51
	v_mul_f32_e32 v56, v61, v23
	v_mul_f32_e32 v58, v63, v27
	v_add_f32_e32 v48, v53, v55
	v_add_f32_e32 v59, 0, v59
	v_fmac_f32_e32 v56, v60, v22
	v_fmac_f32_e32 v58, v62, v26
	v_add_f32_e32 v59, v59, v48
	v_add_f32_e32 v57, v59, v57
	v_add_f32_e32 v56, v56, v58
	v_add_f32_e32 v48, v57, v56
	s_waitcnt vmcnt(24)
	v_mul_f32_e32 v73, v73, v15
	v_mul_f32_e32 v75, v75, v19
	v_mul_f32_e32 v65, v65, v13
	v_mul_f32_e32 v67, v67, v17
	v_mul_f32_e32 v69, v69, v21
	v_mul_f32_e32 v71, v71, v25
	v_fmac_f32_e32 v73, v72, v14
	v_fmac_f32_e32 v75, v74, v18
	v_fmac_f32_e32 v65, v64, v12
	v_fmac_f32_e32 v67, v66, v16
	v_fmac_f32_e32 v69, v68, v20
	v_fmac_f32_e32 v71, v70, v24
	v_add_f32_e32 v73, v73, v75
	v_add_f32_e32 v75, v65, v67
	v_mul_f32_e32 v72, v77, v23
	v_mul_f32_e32 v74, v79, v27
	v_add_f32_e32 v64, v69, v71
	v_add_f32_e32 v75, 0, v75
	v_fmac_f32_e32 v72, v76, v22
	v_fmac_f32_e32 v74, v78, v26
	v_add_f32_e32 v75, v75, v64
	v_add_f32_e32 v73, v75, v73
	v_add_f32_e32 v72, v72, v74
	v_add_f32_e32 v64, v73, v72
	s_waitcnt vmcnt(20)
	v_mul_f32_e32 v89, v89, v15
	v_mul_f32_e32 v91, v91, v19
	v_mul_f32_e32 v81, v81, v13
	v_mul_f32_e32 v83, v83, v17
	v_mul_f32_e32 v85, v85, v21
	v_mul_f32_e32 v87, v87, v25
	v_fmac_f32_e32 v89, v88, v14
	v_fmac_f32_e32 v91, v90, v18
	v_fmac_f32_e32 v81, v80, v12
	v_fmac_f32_e32 v83, v82, v16
	v_fmac_f32_e32 v85, v84, v20
	v_fmac_f32_e32 v87, v86, v24
	v_add_f32_e32 v89, v89, v91
	v_add_f32_e32 v91, v81, v83
	v_mul_f32_e32 v88, v93, v23
	v_mul_f32_e32 v90, v95, v27
	v_add_f32_e32 v80, v85, v87
	v_add_f32_e32 v91, 0, v91
	v_fmac_f32_e32 v88, v92, v22
	v_fmac_f32_e32 v90, v94, v26
	v_add_f32_e32 v91, v91, v80
	v_add_f32_e32 v89, v91, v89
	v_add_f32_e32 v88, v88, v90
	v_add_f32_e32 v80, v89, v88
	s_waitcnt vmcnt(16)
	v_mul_f32_e32 v105, v105, v15
	v_mul_f32_e32 v107, v107, v19
	v_mul_f32_e32 v97, v97, v13
	v_mul_f32_e32 v99, v99, v17
	v_mul_f32_e32 v101, v101, v21
	v_mul_f32_e32 v103, v103, v25
	v_fmac_f32_e32 v105, v104, v14
	v_fmac_f32_e32 v107, v106, v18
	v_fmac_f32_e32 v97, v96, v12
	v_fmac_f32_e32 v99, v98, v16
	v_fmac_f32_e32 v101, v100, v20
	v_fmac_f32_e32 v103, v102, v24
	v_add_f32_e32 v105, v105, v107
	v_add_f32_e32 v107, v97, v99
	v_mul_f32_e32 v104, v109, v23
	v_mul_f32_e32 v106, v111, v27
	v_add_f32_e32 v96, v101, v103
	v_add_f32_e32 v107, 0, v107
	v_fmac_f32_e32 v104, v108, v22
	v_fmac_f32_e32 v106, v110, v26
	v_add_f32_e32 v107, v107, v96
	v_add_f32_e32 v105, v107, v105
	v_add_f32_e32 v104, v104, v106
	v_add_f32_e32 v96, v105, v104
	s_waitcnt vmcnt(12)
	v_mul_f32_e32 v121, v121, v15
	v_mul_f32_e32 v123, v123, v19
	v_mul_f32_e32 v113, v113, v13
	v_mul_f32_e32 v115, v115, v17
	v_mul_f32_e32 v117, v117, v21
	v_mul_f32_e32 v119, v119, v25
	v_fmac_f32_e32 v121, v120, v14
	v_fmac_f32_e32 v123, v122, v18
	v_fmac_f32_e32 v113, v112, v12
	v_fmac_f32_e32 v115, v114, v16
	v_fmac_f32_e32 v117, v116, v20
	v_fmac_f32_e32 v119, v118, v24
	v_add_f32_e32 v121, v121, v123
	v_add_f32_e32 v123, v113, v115
	v_mul_f32_e32 v120, v125, v23
	v_mul_f32_e32 v122, v127, v27
	v_add_f32_e32 v112, v117, v119
	v_add_f32_e32 v123, 0, v123
	v_fmac_f32_e32 v120, v124, v22
	v_fmac_f32_e32 v122, v126, v26
	v_add_f32_e32 v123, v123, v112
	v_add_f32_e32 v121, v123, v121
	v_add_f32_e32 v120, v120, v122
	v_add_f32_e32 v112, v121, v120
	s_waitcnt vmcnt(8)
	v_mul_f32_e32 v137, v137, v15
	v_mul_f32_e32 v139, v139, v19
	v_mul_f32_e32 v129, v129, v13
	v_mul_f32_e32 v131, v131, v17
	v_mul_f32_e32 v133, v133, v21
	v_mul_f32_e32 v135, v135, v25
	v_fmac_f32_e32 v137, v136, v14
	v_fmac_f32_e32 v139, v138, v18
	v_fmac_f32_e32 v129, v128, v12
	v_fmac_f32_e32 v131, v130, v16
	v_fmac_f32_e32 v133, v132, v20
	v_fmac_f32_e32 v135, v134, v24
	v_add_f32_e32 v137, v137, v139
	v_add_f32_e32 v139, v129, v131
	v_mul_f32_e32 v136, v141, v23
	v_mul_f32_e32 v138, v143, v27
	v_add_f32_e32 v128, v133, v135
	v_add_f32_e32 v139, 0, v139
	v_fmac_f32_e32 v136, v140, v22
	v_fmac_f32_e32 v138, v142, v26
	v_add_f32_e32 v139, v139, v128
	v_add_f32_e32 v137, v139, v137
	v_add_f32_e32 v136, v136, v138
	v_add_f32_e32 v128, v137, v136
	s_waitcnt vmcnt(4)
	v_mul_f32_e32 v153, v153, v15
	v_mul_f32_e32 v155, v155, v19
	v_mul_f32_e32 v145, v145, v13
	v_mul_f32_e32 v147, v147, v17
	v_mul_f32_e32 v149, v149, v21
	v_mul_f32_e32 v151, v151, v25
	v_fmac_f32_e32 v153, v152, v14
	v_fmac_f32_e32 v155, v154, v18
	v_fmac_f32_e32 v145, v144, v12
	v_fmac_f32_e32 v147, v146, v16
	v_fmac_f32_e32 v149, v148, v20
	v_fmac_f32_e32 v151, v150, v24
	v_add_f32_e32 v153, v153, v155
	v_add_f32_e32 v155, v145, v147
	v_mul_f32_e32 v152, v157, v23
	v_mul_f32_e32 v154, v159, v27
	v_add_f32_e32 v144, v149, v151
	v_add_f32_e32 v155, 0, v155
	v_fmac_f32_e32 v152, v156, v22
	v_fmac_f32_e32 v154, v158, v26
	v_add_f32_e32 v155, v155, v144
	v_add_f32_e32 v153, v155, v153
	v_add_f32_e32 v152, v152, v154
	v_add_f32_e32 v144, v153, v152
	s_waitcnt vmcnt(0)
	v_mul_f32_e32 v169, v169, v15
	v_mul_f32_e32 v171, v171, v19
	v_mul_f32_e32 v161, v161, v13
	v_mul_f32_e32 v163, v163, v17
	v_mul_f32_e32 v165, v165, v21
	v_mul_f32_e32 v167, v167, v25
	v_fmac_f32_e32 v169, v168, v14
	v_fmac_f32_e32 v171, v170, v18
	v_fmac_f32_e32 v161, v160, v12
	v_fmac_f32_e32 v163, v162, v16
	v_fmac_f32_e32 v165, v164, v20
	v_fmac_f32_e32 v167, v166, v24
	v_add_f32_e32 v169, v169, v171
	v_add_f32_e32 v171, v161, v163
	v_mul_f32_e32 v168, v173, v23
	v_mul_f32_e32 v170, v175, v27
	v_add_f32_e32 v160, v165, v167
	v_add_f32_e32 v171, 0, v171
	v_fmac_f32_e32 v168, v172, v22
	v_fmac_f32_e32 v170, v174, v26
	v_add_f32_e32 v171, v171, v160
	v_add_f32_e32 v169, v171, v169
	v_add_f32_e32 v168, v168, v170
	v_add_f32_e32 v160, v169, v168
	ds_bpermute_b32 v49, v6, v48
	ds_bpermute_b32 v65, v6, v64
	ds_bpermute_b32 v81, v6, v80
	ds_bpermute_b32 v97, v6, v96
	ds_bpermute_b32 v113, v6, v112
	ds_bpermute_b32 v129, v6, v128
	ds_bpermute_b32 v145, v6, v144
	ds_bpermute_b32 v161, v6, v160
	s_waitcnt lgkmcnt(0)
	v_add_f32_e32 v48, v48, v49
	v_add_f32_e32 v64, v64, v65
	v_add_f32_e32 v80, v80, v81
	v_add_f32_e32 v96, v96, v97
	v_add_f32_e32 v112, v112, v113
	v_add_f32_e32 v128, v128, v129
	v_add_f32_e32 v144, v144, v145
	v_add_f32_e32 v160, v160, v161
	ds_bpermute_b32 v49, v7, v48
	ds_bpermute_b32 v65, v7, v64
	ds_bpermute_b32 v81, v7, v80
	ds_bpermute_b32 v97, v7, v96
	ds_bpermute_b32 v113, v7, v112
	ds_bpermute_b32 v129, v7, v128
	ds_bpermute_b32 v145, v7, v144
	ds_bpermute_b32 v161, v7, v160
	s_waitcnt lgkmcnt(0)
	v_add_f32_e32 v48, v48, v49
	v_add_f32_e32 v64, v64, v65
	v_add_f32_e32 v80, v80, v81
	v_add_f32_e32 v96, v96, v97
	v_add_f32_e32 v112, v112, v113
	v_add_f32_e32 v128, v128, v129
	v_add_f32_e32 v144, v144, v145
	v_add_f32_e32 v160, v160, v161
	ds_bpermute_b32 v49, v8, v48
	ds_bpermute_b32 v65, v8, v64
	ds_bpermute_b32 v81, v8, v80
	ds_bpermute_b32 v97, v8, v96
	ds_bpermute_b32 v113, v8, v112
	ds_bpermute_b32 v129, v8, v128
	ds_bpermute_b32 v145, v8, v144
	ds_bpermute_b32 v161, v8, v160
	s_waitcnt lgkmcnt(0)
	v_add_f32_e32 v48, v48, v49
	v_add_f32_e32 v64, v64, v65
	v_add_f32_e32 v80, v80, v81
	v_add_f32_e32 v96, v96, v97
	v_add_f32_e32 v112, v112, v113
	v_add_f32_e32 v128, v128, v129
	v_add_f32_e32 v144, v144, v145
	v_add_f32_e32 v160, v160, v161
	ds_bpermute_b32 v49, v9, v48
	ds_bpermute_b32 v65, v9, v64
	ds_bpermute_b32 v81, v9, v80
	ds_bpermute_b32 v97, v9, v96
	ds_bpermute_b32 v113, v9, v112
	ds_bpermute_b32 v129, v9, v128
	ds_bpermute_b32 v145, v9, v144
	ds_bpermute_b32 v161, v9, v160
	s_waitcnt lgkmcnt(0)
	v_add_f32_e32 v48, v48, v49
	v_add_f32_e32 v64, v64, v65
	v_add_f32_e32 v80, v80, v81
	v_add_f32_e32 v96, v96, v97
	v_add_f32_e32 v112, v112, v113
	v_add_f32_e32 v128, v128, v129
	v_add_f32_e32 v144, v144, v145
	v_add_f32_e32 v160, v160, v161
	ds_bpermute_b32 v49, v10, v48
	ds_bpermute_b32 v65, v10, v64
	ds_bpermute_b32 v81, v10, v80
	ds_bpermute_b32 v97, v10, v96
	ds_bpermute_b32 v113, v10, v112
	ds_bpermute_b32 v129, v10, v128
	ds_bpermute_b32 v145, v10, v144
	ds_bpermute_b32 v161, v10, v160
	s_waitcnt lgkmcnt(0)
	v_add_f32_e32 v48, v48, v49
	v_add_f32_e32 v64, v64, v65
	v_add_f32_e32 v80, v80, v81
	v_add_f32_e32 v96, v96, v97
	v_add_f32_e32 v112, v112, v113
	v_add_f32_e32 v128, v128, v129
	v_add_f32_e32 v144, v144, v145
	v_add_f32_e32 v160, v160, v161
	ds_bpermute_b32 v49, v11, v48
	ds_bpermute_b32 v65, v11, v64
	ds_bpermute_b32 v81, v11, v80
	ds_bpermute_b32 v97, v11, v96
	ds_bpermute_b32 v113, v11, v112
	ds_bpermute_b32 v129, v11, v128
	ds_bpermute_b32 v145, v11, v144
	ds_bpermute_b32 v161, v11, v160
	s_waitcnt lgkmcnt(0)
	v_add_f32_e32 v48, v48, v49
	v_add_f32_e32 v64, v64, v65
	v_add_f32_e32 v80, v80, v81
	v_add_f32_e32 v96, v96, v97
	v_add_f32_e32 v112, v112, v113
	v_add_f32_e32 v128, v128, v129
	v_add_f32_e32 v144, v144, v145
	v_add_f32_e32 v160, v160, v161
	s_and_saveexec_b64 s[36:37], s[2:3]
	s_add_u32 s38, s18, s34
	s_addc_u32 s39, s19, s35
	global_store_dword v1, v48, s[38:39]
	s_add_u32 s34, s34, 0x1c00
	s_addc_u32 s35, s35, 0
	s_add_u32 s38, s18, s34
	s_addc_u32 s39, s19, s35
	global_store_dword v1, v64, s[38:39]
	s_add_u32 s34, s34, 0x1c00
	s_addc_u32 s35, s35, 0
	s_add_u32 s38, s18, s34
	s_addc_u32 s39, s19, s35
	global_store_dword v1, v80, s[38:39]
	s_add_u32 s34, s34, 0x1c00
	s_addc_u32 s35, s35, 0
	s_add_u32 s38, s18, s34
	s_addc_u32 s39, s19, s35
	global_store_dword v1, v96, s[38:39]
	s_add_u32 s34, s34, 0x1c00
	s_addc_u32 s35, s35, 0
	s_add_u32 s38, s18, s34
	s_addc_u32 s39, s19, s35
	global_store_dword v1, v112, s[38:39]
	s_add_u32 s34, s34, 0x1c00
	s_addc_u32 s35, s35, 0
	s_add_u32 s38, s18, s34
	s_addc_u32 s39, s19, s35
	global_store_dword v1, v128, s[38:39]
	s_add_u32 s34, s34, 0x1c00
	s_addc_u32 s35, s35, 0
	s_add_u32 s38, s18, s34
	s_addc_u32 s39, s19, s35
	global_store_dword v1, v144, s[38:39]
	s_add_u32 s34, s34, 0x1c00
	s_addc_u32 s35, s35, 0
	s_add_u32 s38, s18, s34
	s_addc_u32 s39, s19, s35
	global_store_dword v1, v160, s[38:39]
	s_add_u32 s34, s34, 0x1c00
	s_addc_u32 s35, s35, 0
	s_or_b64 exec, exec, s[36:37]
	v_lshl_add_u64 v[4:5], v[4:5], 0, s[46:47]
	s_add_i32 s11, s11, -1
	s_cmp_eq_u32 s11, 0
	s_cbranch_scc0 .LBB0_230
	s_branch .LBB0_227

.LBB0_1249:
	s_lshl_b64 s[40:41], s[10:11], 9
	s_waitcnt lgkmcnt(0)
	v_lshl_add_u64 v[10:11], v[2:3], 0, s[40:41]
	global_load_dwordx2 v[10:11], v[10:11], off
	v_mov_b32_e32 v0, 0
	v_mov_b32_e32 v31, 0
	v_mov_b32_e32 v38, 0
	s_and_saveexec_b64 s[40:41], s[4:5]
	s_cbranch_execz .LBB0_1251
	v_lshl_add_u64 v[32:33], v[4:5], 0, s[38:39]
	global_load_dword v31, v[32:33], off
	global_load_dword v38, v[6:7], off
	v_lshl_or_b32 v42, s49, 5, v12
	v_mov_b32_e32 v43, 0
	v_lshl_add_u64 v[44:45], v[42:43], 2, s[18:19]
	global_load_dword v39, v[44:45], off offset:64
	global_load_dword v40, v[44:45], off
.LBB0_1251:
	s_or_b64 exec, exec, s[40:41]
	s_add_u32 s36, s8, s36
	s_addc_u32 s37, s9, s37
	s_lshl_b64 s[34:35], s[34:35], 10
	s_add_u32 s34, s36, s34
	s_addc_u32 s35, s37, s35
	s_lshl_b64 s[36:37], s[16:17], 2
	s_add_u32 s36, s42, s36
	s_addc_u32 s37, s43, s37
	global_load_dword v35, v1, s[36:37]
	s_waitcnt vmcnt(4)
	v_mul_f32_e32 v36, v31, v31
	v_lshlrev_b32_e32 v34, 16, v11
	v_lshlrev_b32_e32 v32, 16, v10
	v_and_b32_e32 v33, 0xffff0000, v10
	v_add_f32_dpp v36, v36, v36 quad_perm:[1,0,3,2] row_mask:0xf bank_mask:0xf
	s_nop 1
	v_add_f32_dpp v36, v36, v36 quad_perm:[2,3,0,1] row_mask:0xf bank_mask:0xf
	s_nop 1
	v_add_f32_dpp v36, v36, v36 row_half_mirror row_mask:0xf bank_mask:0xf
	s_nop 1
	v_add_f32_dpp v36, v36, v36 row_mirror row_mask:0xf bank_mask:0xf
	ds_bpermute_b32 v37, v29, v36
	s_waitcnt lgkmcnt(0)
	v_add_f32_e32 v10, v36, v37
	s_waitcnt vmcnt(0)
	v_fmamk_f32 v35, v35, 0x3b800000, v14
	v_mul_f32_e32 v37, 0x4b800000, v35
	v_cmp_gt_f32_e32 vcc, s46, v35
	s_nop 1
	v_cndmask_b32_e32 v35, v35, v37, vcc
	v_rsq_f32_e32 v37, v35
	v_and_b32_e32 v35, 0xffff0000, v11
	v_mul_f32_e32 v36, 0x45800000, v37
	v_cndmask_b32_e32 v36, v37, v36, vcc
	v_pk_mul_f32 v[34:35], v[36:37], v[34:35] op_sel_hi:[0,1]
	v_pk_mul_f32 v[32:33], v[36:37], v[32:33] op_sel_hi:[0,1]
	global_store_dwordx4 v15, v[32:35], s[34:35] nt
	v_fmamk_f32 v10, v10, 0x3d000000, v14
	v_mul_f32_e32 v11, 0x4b800000, v10
	v_cmp_gt_f32_e32 vcc, s46, v10
	s_nop 1
	v_cndmask_b32_e32 v10, v10, v11, vcc
	v_rsq_f32_e32 v10, v10
	s_nop 0
	v_mul_f32_e32 v11, 0x45800000, v10
	v_cndmask_b32_e32 v10, v10, v11, vcc
	v_mul_f32_e32 v10, v31, v10
	s_waitcnt vmcnt(1)
	v_mul_f32_e32 v10, v10, v38
	ds_bpermute_b32 v11, v29, v10
	s_and_saveexec_b64 s[34:35], s[4:5]
	s_cbranch_execz .LBB0_1243
	s_add_u32 s16, s8, s30
	s_addc_u32 s30, s9, s31
	s_add_u32 s28, s16, s28
	s_addc_u32 s29, s30, s29
	s_lshl_b64 s[10:11], s[10:11], 6
	s_waitcnt vmcnt(1) lgkmcnt(0)
	v_mul_f32_e32 v0, v39, v11
	v_cndmask_b32_e64 v0, v0, -v0, s[6:7]
	s_waitcnt vmcnt(1)
	v_fmac_f32_e32 v0, v10, v40
	global_store_dword v16, v0, s[28:29]
	v_cvt_pk_bf16_f32 v0, v0, s0
	v_lshl_add_u64 v[10:11], v[8:9], 0, s[10:11]
	global_store_short v[10:11], v0, off
	s_branch .LBB0_1243

.LBB0_1324:
	s_cmp_lt_u32 s74, 8
	s_cselect_b64 s[2:3], -1, 0
	s_and_b64 s[2:3], s[30:31], s[2:3]
	s_cmp_eq_u32 s73, 3
	s_cselect_b64 s[4:5], -1, 0
	s_and_b64 s[2:3], s[2:3], s[4:5]
	s_and_b64 vcc, exec, s[2:3]
	s_cbranch_vccnz .LBB0_1312
	v_mov_b32_e32 v163, v181
	s_lshl_b32 s2, s75, 7
	v_ashrrev_i32_e32 v21, 6, v163
	s_and_b32 s48, s2, 0xfffff800
	v_readfirstlane_b32 s41, v21
	s_lshl_b32 s2, s73, 8
	s_ashr_i32 s77, s41, 1
	s_lshl_b32 s3, s41, 5
	s_add_i32 s4, s48, s2
	s_lshl_b32 s2, s77, 6
	s_and_b32 s3, s3, 32
	s_lshl_b32 s76, s73, 2
	s_and_b32 s79, s75, 15
	s_or_b32 s5, s2, s3
	s_cmpk_lt_i32 s5, 0x100
	s_cselect_b64 s[42:43], -1, 0
	s_cmpk_gt_i32 s5, 0xff
	s_cselect_b64 s[44:45], -1, 0
	s_and_b64 s[2:3], s[44:45], exec
	s_cselect_b32 s2, 0, s5
	v_and_b32_e32 v162, 31, v163
	s_add_i32 s40, s4, s2
	v_or_b32_e32 v3, s40, v162
	v_mov_b64_e32 v[0:1], s[16:17]
	s_ashr_i32 s49, s48, 31
	v_mad_i64_i32 v[0:1], s[2:3], v3, s67, v[0:1]
	s_lshl_b64 s[4:5], s[48:49], 11
	s_add_u32 s2, s56, s4
	s_addc_u32 s3, s57, s5
	s_lshl_b32 s78, s79, 7
	v_bfe_u32 v2, v163, 5, 1
	s_mul_i32 s34, s79, 0xc0
	s_add_u32 s2, s2, s78
	v_lshl_add_u64 v[0:1], v[0:1], 0, s[34:35]
	v_lshlrev_b32_e32 v144, 4, v2
	s_addc_u32 s3, s3, 0
	s_lshl_b64 s[82:83], s[48:49], 11
	s_add_u32 s82, s82, s78
	s_addc_u32 s83, s83, 0
	s_add_u32 s84, s82, 0x2dc00000
	s_addc_u32 s85, s83, 0
	s_add_u32 s82, s82, 0x23b00000
	s_addc_u32 s83, s83, 0
	s_add_u32 s82, s82, s8
	s_addc_u32 s83, s83, s9
	s_add_u32 s84, s84, s8
	s_addc_u32 s85, s85, s9
	s_lshl_b64 s[86:87], s[48:49], 6
	s_add_u32 s86, s86, 0xc200000
	s_addc_u32 s87, s87, 0
	s_add_u32 s86, s86, s8
	s_addc_u32 s87, s87, s9
	s_lshr_b32 s88, s41, 2
	s_lshl_b32 s89, s88, 17
	s_add_u32 s82, s82, s89
	s_addc_u32 s83, s83, 0
	s_add_u32 s84, s84, s89
	s_addc_u32 s85, s85, 0
	s_lshl_b32 s89, s88, 12
	s_add_u32 s86, s86, s89
	s_addc_u32 s87, s87, 0
	s_or_b32 s34, s76, 3
	v_lshl_add_u64 v[0:1], v[0:1], 0, v[144:145]
	s_min_i32 s52, s34, 0
	global_load_dwordx4 v[100:103], v[0:1], off
	global_load_dwordx4 v[96:99], v[0:1], off offset:32
	global_load_dwordx4 v[92:95], v[0:1], off offset:64
	global_load_dwordx4 v[88:91], v[0:1], off offset:96
	global_load_dwordx4 v[84:87], v[0:1], off offset:128
	global_load_dwordx4 v[80:83], v[0:1], off offset:160
	global_load_dwordx4 v[220:223], v211, s[82:83]
	global_load_dwordx4 v[224:227], v218, s[82:83]
	global_load_dwordx2 v[228:229], v212, s[84:85]
	global_load_dwordx2 v[230:231], v212, s[84:85] offset:2048
	global_load_dwordx2 v[232:233], v217, s[84:85]
	global_load_dwordx2 v[234:235], v217, s[84:85] offset:2048
	global_load_dwordx4 v[236:239], v213, s[86:87]
	s_add_u32 s82, s82, 0x40000
	s_addc_u32 s83, s83, 0
	s_add_u32 s84, s84, 0x40000
	s_addc_u32 s85, s85, 0
	s_add_u32 s86, s86, 0x2000
	s_addc_u32 s87, s87, 0
	s_ashr_i32 s53, s52, 31
	s_lshl_b64 s[46:47], s[48:49], 6
	v_and_b32_e32 v161, 7, v163
	s_lshl_b64 s[50:51], s[52:53], 17
	v_ashrrev_i32_e32 v17, 3, v163
	v_lshlrev_b32_e32 v166, 4, v161
	s_add_u32 s2, s2, s50
	v_lshl_or_b32 v16, v17, 11, v166
	v_mov_b32_e32 v0, v145
	v_mov_b32_e32 v1, v145
	v_mov_b32_e32 v2, v145
	v_mov_b32_e32 v3, v145
	v_mov_b32_e32 v4, v145
	v_mov_b32_e32 v5, v145
	v_mov_b32_e32 v6, v145
	v_mov_b32_e32 v7, v145
	v_mov_b32_e32 v8, v145
	v_mov_b32_e32 v9, v145
	v_mov_b32_e32 v10, v145
	v_mov_b32_e32 v11, v145
	v_mov_b32_e32 v12, v145
	v_mov_b32_e32 v13, v145
	v_mov_b32_e32 v14, v145
	v_mov_b32_e32 v15, v145
	s_addc_u32 s3, s3, s51
	v_add_u32_e32 v19, 0xffffff00, v163
	v_ashrrev_i32_e32 v22, 2, v19
	v_and_b32_e32 v18, 3, v163
	v_lshlrev_b32_e32 v19, 6, v22
	v_and_b32_e32 v19, 0xfc0, v19
	v_lshlrev_b32_e32 v20, 4, v18
	v_cmp_lt_i32_e64 s[2:3], s65, v163
	s_and_saveexec_b64 s[54:55], s[2:3]
	s_xor_b64 s[54:55], exec, s[54:55]
	s_cbranch_execz .LBB0_1327
	s_add_u32 s34, s58, s46
	s_addc_u32 s80, s59, s47
	s_lshl_b64 s[52:53], s[52:53], 12
	s_add_u32 s52, s34, s52
	v_or_b32_e32 v23, v19, v20
	s_addc_u32 s53, s80, s53

.LBB0_1329:
	s_or_b64 exec, exec, s[52:53]
	v_mul_lo_u32 v167, v17, s68
	v_add3_u32 v17, 0, v167, v166
	v_lshlrev_b32_e32 v17, 4, v163
	v_mul_lo_u32 v168, v22, s69
	v_and_b32_e32 v169, 48, v17
	s_and_saveexec_b64 s[48:49], s[2:3]
	s_xor_b64 s[48:49], exec, s[48:49]
	v_add3_u32 v17, 0, v168, v169
	s_or_saveexec_b64 s[48:49], s[48:49]
	v_bfrev_b32_e32 v17, v163
	v_lshrrev_b32_e32 v17, 30, v17
	v_or_b32_e32 v17, v24, v17
	v_lshlrev_b32_e32 v170, 3, v17
	v_mul_u32_u24_e32 v172, 0x90, v23
	s_xor_b64 exec, exec, s[48:49]
	s_cbranch_execz .LBB0_1333
	v_add3_u32 v17, 0, v170, v172
	v_perm_b32 v22, v148, v146, s70
	v_perm_b32 v23, v152, v150, s70
	v_perm_b32 v24, v148, v146, s71
	v_perm_b32 v25, v152, v150, s71
	v_add_u32_e32 v17, 0x2000, v17
	v_perm_b32 v22, v149, v147, s70
	v_perm_b32 v23, v153, v151, s70
	v_perm_b32 v24, v149, v147, s71
	v_perm_b32 v25, v153, v151, s71
.LBB0_1333:
	s_or_b64 exec, exec, s[48:49]
	s_cmp_eq_u32 s88, 0
	s_cbranch_scc0 .Lp9m_pro_g1
	s_waitcnt vmcnt(0)
	ds_write_b128 v214, v[220:223]
	ds_write_b128 v214, v[224:227] offset:4608
	v_perm_b32 v240, v230, v228, s70
	v_perm_b32 v241, v234, v232, s70
	v_perm_b32 v242, v230, v228, s71
	v_perm_b32 v243, v234, v232, s71
	ds_write2_b64 v215, v[240:241], v[242:243] offset0:128 offset1:146
	v_perm_b32 v244, v231, v229, s70
	v_perm_b32 v245, v235, v233, s70
	v_perm_b32 v246, v231, v229, s71
	v_perm_b32 v247, v235, v233, s71
	ds_write2_b64 v215, v[244:245], v[246:247] offset0:164 offset1:182
	ds_write_b128 v216, v[236:239]
	s_branch .Lp9m_pro_done
